# attention: NA bias section rewritten branch-free with batched LDS reads; QK/PV LDS fragment reads issued 3-4 deep ahead with counted lgkmcnt; Q-load wait hoisted out of blk loop
# speedup vs baseline: 1.0088x; 1.0088x over previous
.LBB0_280:
	s_or_b64 exec, exec, s[46:47]
	s_lshl_b32 s70, s43, 8
	s_add_i32 s70, s70, 0x8000
	s_lshl_b32 s43, s57, 6
	s_ashr_i32 s45, s44, 31
	s_sub_i32 s43, s70, s43
	v_add_u32_e32 v0, s56, v140
	v_lshl_add_u64 v[2:3], s[44:45], 1, v[132:133]
	s_cmp_gt_i32 s57, 0
	v_mad_i64_i32 v[4:5], s[44:45], v0, s79, v[2:3]
	v_add_u32_e32 v0, 16, v0
	s_cselect_b32 s48, s67, s43
	v_mad_i64_i32 v[2:3], s[44:45], v0, s79, v[2:3]
	v_add_u32_e32 v0, s48, v142
	global_load_dwordx4 v[68:71], v[4:5], off
	global_load_dwordx4 v[72:75], v[4:5], off offset:64
	global_load_dwordx4 v[76:79], v[4:5], off offset:128
	global_load_dwordx4 v[80:83], v[4:5], off offset:192
	v_mad_i64_i32 v[4:5], s[44:45], v0, s79, v[136:137]
	s_mov_b32 s43, s21
	s_lshl_b64 s[44:45], s[20:21], 1
	v_lshl_add_u64 v[6:7], v[4:5], 0, s[44:45]
	s_lshl_b64 s[46:47], s[42:43], 1
	v_lshl_add_u64 v[4:5], v[4:5], 0, s[46:47]
	global_load_dwordx4 v[100:103], v[6:7], off
	global_load_dwordx4 v[104:107], v[4:5], off
	v_add_u32_e32 v0, s48, v143
	v_mad_i64_i32 v[4:5], s[42:43], v0, s79, v[136:137]
	v_lshl_add_u64 v[6:7], v[4:5], 0, s[44:45]
	v_lshl_add_u64 v[4:5], v[4:5], 0, s[46:47]
	global_load_dwordx4 v[108:111], v[6:7], off
	global_load_dwordx4 v[112:115], v[4:5], off
	global_load_dwordx4 v[84:87], v[2:3], off
	global_load_dwordx4 v[88:91], v[2:3], off offset:64
	global_load_dwordx4 v[92:95], v[2:3], off offset:128
	global_load_dwordx4 v[96:99], v[2:3], off offset:192
	s_cmp_lt_i32 s57, -3
	s_waitcnt vmcnt(7)
	ds_write_b128 v187, v[100:103]
	s_waitcnt vmcnt(6)
	ds_write_b128 v188, v[104:107] offset:32768
	s_waitcnt vmcnt(5)
	ds_write_b128 v189, v[108:111]
	s_waitcnt vmcnt(4)
	ds_write_b128 v190, v[112:115] offset:32768
	s_waitcnt lgkmcnt(0)
	s_barrier
	s_cbranch_scc1 .LBB0_256
	v_add_u32_e32 v226, s62, v140
	v_max_i32_e32 v0, 8, v226
	v_add_u32_e32 v0, -8, v0
	v_add_u32_e32 v230, 16, v226
	v_min_u32_e32 v228, 48, v0
	v_max_i32_e32 v0, 8, v230
	v_add_u32_e32 v0, -8, v0
	v_mov_b32_e32 v2, v1
	v_mov_b32_e32 v3, v1
	v_min_u32_e32 v231, 48, v0
	v_mov_b32_e32 v0, v1
	v_mov_b32_e32 v138, 0
	v_mov_b64_e32 v[10:11], v[2:3]
	v_mov_b64_e32 v[42:43], v[2:3]
	v_mov_b64_e32 v[14:15], v[2:3]
	v_mov_b64_e32 v[46:47], v[2:3]
	v_mov_b64_e32 v[18:19], v[2:3]
	v_mov_b64_e32 v[50:51], v[2:3]
	v_mov_b64_e32 v[22:23], v[2:3]
	v_mov_b64_e32 v[54:55], v[2:3]
	v_mov_b64_e32 v[26:27], v[2:3]
	v_mov_b64_e32 v[58:59], v[2:3]
	v_mov_b64_e32 v[30:31], v[2:3]
	v_mov_b64_e32 v[62:63], v[2:3]
	v_mov_b64_e32 v[34:35], v[2:3]
	v_mov_b64_e32 v[66:67], v[2:3]
	v_mov_b64_e32 v[38:39], v[2:3]
	v_mov_b64_e32 v[6:7], v[2:3]
	s_mov_b64 s[90:91], s[76:77]
	s_add_i32 s20, s57, 4
	s_add_i32 s71, s69, 7
	s_add_i32 s72, s62, 0xffffff80
	s_add_i32 s73, s62, 0x9f
	s_add_i32 s74, s62, 0xffffff9f
	s_add_i32 s75, s62, 0x61
	v_sub_u32_e32 v227, v162, v226
	v_add_u32_e32 v229, 16, v228
	v_add_u32_e32 v232, 16, v231
	s_mov_b32 s60, 0
	v_mov_b32_e32 v234, 0xf0c9f2ca
	v_mov_b64_e32 v[8:9], v[0:1]
	v_mov_b64_e32 v[40:41], v[0:1]
	v_mov_b64_e32 v[12:13], v[0:1]
	v_mov_b64_e32 v[44:45], v[0:1]
	v_mov_b64_e32 v[16:17], v[0:1]
	v_mov_b64_e32 v[48:49], v[0:1]
	v_mov_b64_e32 v[20:21], v[0:1]
	v_mov_b64_e32 v[52:53], v[0:1]
	v_mov_b64_e32 v[24:25], v[0:1]
	v_mov_b64_e32 v[56:57], v[0:1]
	v_mov_b64_e32 v[28:29], v[0:1]
	v_mov_b64_e32 v[60:61], v[0:1]
	v_mov_b64_e32 v[32:33], v[0:1]
	v_mov_b64_e32 v[64:65], v[0:1]
	v_mov_b32_e32 v235, 0xf0c9f2ca
	v_mov_b64_e32 v[36:37], v[0:1]
	v_mov_b64_e32 v[4:5], v[0:1]
	v_mov_b32_e32 v139, v138
	s_waitcnt vmcnt(0)

.LBB0_287:
	s_andn2_b64 vcc, exec, s[42:43]
	s_cbranch_vccnz .LBB0_333
	s_lshl_b32 s85, s86, 13
	s_add_i32 s42, s77, s85
	v_add3_u32 v0, s42, v150, v149
	v_add3_u32 v2, s42, v152, v149
	ds_read_b128 v[236:239], v0
	ds_read_b128 v[240:243], v0 offset:1024
	ds_read_b128 v[244:247], v2
	ds_read_b128 v[248:251], v2 offset:1024
	v_add3_u32 v0, s42, v156, v149
	v_add3_u32 v2, s42, v158, v149
	s_andn2_b64 vcc, exec, s[50:51]
	s_waitcnt lgkmcnt(3)
	v_mfma_f32_16x16x32_bf16 v[128:131], v[236:239], v[68:71], 0
	v_mfma_f32_16x16x32_bf16 v[120:123], v[236:239], v[84:87], 0
	ds_read_b128 v[236:239], v0
	s_waitcnt lgkmcnt(3)
	v_mfma_f32_16x16x32_bf16 v[124:127], v[240:243], v[68:71], 0
	v_mfma_f32_16x16x32_bf16 v[116:119], v[240:243], v[84:87], 0
	ds_read_b128 v[240:243], v0 offset:1024
	s_waitcnt lgkmcnt(3)
	v_mfma_f32_16x16x32_bf16 v[128:131], v[244:247], v[72:75], v[128:131]
	v_mfma_f32_16x16x32_bf16 v[120:123], v[244:247], v[88:91], v[120:123]
	ds_read_b128 v[244:247], v2
	s_waitcnt lgkmcnt(3)
	v_mfma_f32_16x16x32_bf16 v[124:127], v[248:251], v[72:75], v[124:127]
	v_mfma_f32_16x16x32_bf16 v[116:119], v[248:251], v[88:91], v[116:119]
	ds_read_b128 v[248:251], v2 offset:1024
	s_waitcnt lgkmcnt(3)
	v_mfma_f32_16x16x32_bf16 v[128:131], v[236:239], v[76:79], v[128:131]
	v_mfma_f32_16x16x32_bf16 v[120:123], v[236:239], v[92:95], v[120:123]
	s_waitcnt lgkmcnt(2)
	v_mfma_f32_16x16x32_bf16 v[124:127], v[240:243], v[76:79], v[124:127]
	v_mfma_f32_16x16x32_bf16 v[116:119], v[240:243], v[92:95], v[116:119]
	s_waitcnt lgkmcnt(0)
	v_mfma_f32_16x16x32_bf16 v[128:131], v[244:247], v[80:83], v[128:131]
	v_mfma_f32_16x16x32_bf16 v[124:127], v[248:251], v[80:83], v[124:127]
	v_mfma_f32_16x16x32_bf16 v[120:123], v[244:247], v[96:99], v[120:123]
	v_mfma_f32_16x16x32_bf16 v[116:119], v[248:251], v[96:99], v[116:119]
	s_nop 3
	s_cbranch_vccnz .LBB0_328
	s_andn2_b64 vcc, exec, s[40:41]
	s_mov_b64 s[42:43], -1
	s_cbranch_vccnz .LBB0_293
	s_cmp_lt_i32 s87, s74
	s_cselect_b64 s[42:43], -1, 0
	s_cmp_gt_i32 s87, s75
	s_cselect_b64 s[88:89], -1, 0
	s_or_b64 s[42:43], s[42:43], s[88:89]
	s_andn2_b64 vcc, exec, s[42:43]
	v_mov_b32_e32 v236, v131
	v_mov_b32_e32 v237, v130
	v_mov_b32_e32 v0, v129
	v_mov_b32_e32 v2, v128
	v_mov_b32_e32 v245, v123
	v_mov_b32_e32 v246, v122
	v_mov_b32_e32 v242, v121
	v_mov_b32_e32 v243, v120
	v_mov_b32_e32 v240, v127
	v_mov_b32_e32 v241, v126
	v_mov_b32_e32 v238, v125
	v_mov_b32_e32 v239, v124
	v_mov_b32_e32 v249, v119
	v_mov_b32_e32 v250, v118
	v_mov_b32_e32 v247, v117
	v_mov_b32_e32 v248, v116
	s_cbranch_vccnz .LBB0_292
	v_add_u32_e32 v249, s87, v227
	v_cmp_gt_u32_e32 vcc, s83, v249
	v_add_u32_e32 v0, 1, v249
	v_add_u32_e32 v236, 2, v249
	v_cndmask_b32_e32 v2, v218, v128, vcc
	v_cmp_gt_u32_e32 vcc, s83, v0
	v_add_u32_e32 v238, -16, v249
	v_add_u32_e32 v240, 6, v249
	v_cndmask_b32_e32 v0, v218, v129, vcc
	v_cmp_gt_u32_e32 vcc, s83, v236
	v_add_u32_e32 v236, 3, v249
	v_add_u32_e32 v247, -12, v249
	v_cndmask_b32_e32 v237, v218, v130, vcc
	v_cmp_gt_u32_e32 vcc, s83, v236
	v_add_u32_e32 v250, -10, v249
	s_nop 0
	v_cndmask_b32_e32 v236, v218, v131, vcc
	v_cmp_gt_u32_e32 vcc, s83, v238
	v_add_u32_e32 v238, -15, v249
	s_nop 0
	v_cndmask_b32_e32 v243, v218, v120, vcc
	v_cmp_gt_u32_e32 vcc, s83, v238
	v_add_u32_e32 v238, -14, v249
	s_nop 0
	v_cndmask_b32_e32 v242, v218, v121, vcc
	v_cmp_gt_u32_e32 vcc, s83, v238
	v_add_u32_e32 v238, -13, v249
	s_nop 0
	v_cndmask_b32_e32 v246, v218, v122, vcc
	v_cmp_gt_u32_e32 vcc, s83, v238
	v_add_u32_e32 v238, 4, v249
	s_nop 0
	v_cndmask_b32_e32 v245, v218, v123, vcc
	v_cmp_gt_u32_e32 vcc, s83, v238
	v_add_u32_e32 v238, 5, v249
	s_nop 0
	v_cndmask_b32_e32 v239, v218, v124, vcc
	v_cmp_gt_u32_e32 vcc, s83, v238
	s_nop 1
	v_cndmask_b32_e32 v238, v218, v125, vcc
	v_cmp_gt_u32_e32 vcc, s83, v240
	v_add_u32_e32 v240, 7, v249
	s_nop 0
	v_cndmask_b32_e32 v241, v218, v126, vcc
	v_cmp_gt_u32_e32 vcc, s83, v240
	s_nop 1
	v_cndmask_b32_e32 v240, v218, v127, vcc
	v_cmp_gt_u32_e32 vcc, s83, v247
	v_add_u32_e32 v247, -11, v249
	v_add_u32_e32 v249, -9, v249
	v_cndmask_b32_e32 v248, v218, v116, vcc
	v_cmp_gt_u32_e32 vcc, s83, v247
	s_nop 1
	v_cndmask_b32_e32 v247, v218, v117, vcc
	v_cmp_gt_u32_e32 vcc, s83, v250
	s_nop 1
	v_cndmask_b32_e32 v250, v218, v118, vcc
	v_cmp_gt_u32_e32 vcc, s83, v249
	s_nop 1
	v_cndmask_b32_e32 v249, v218, v119, vcc

.LBB0_293:
	s_andn2_b64 vcc, exec, s[42:43]
	s_cbranch_vccnz .LBB0_327
	v_subrev_u32_e32 v0, s68, v233
	s_movk_i32 s42, 0x7c
	v_lshl_or_b32 v245, s86, 5, v159
	v_mul_lo_u32 v0, v0, s42
	v_sub_u32_e32 v2, v245, v226
	v_sub_u32_e32 v244, v245, v230
	v_add_u32_e32 v0, 0x10000, v0
	v_lshl_add_u32 v2, v2, 2, v0
	v_lshl_add_u32 v0, v244, 2, v0
	ds_read2_b32 v[242:243], v0 offset0:233 offset1:232
	ds_read2_b32 v[246:247], v0 offset0:234 offset1:237
	ds_read2_b32 v[248:249], v0 offset0:236 offset1:239
	ds_read_b32 v245, v0 offset:940
	ds_read_b32 v250, v0 offset:952
	ds_read2_b32 v[236:237], v2 offset0:235 offset1:234
	ds_read2_b32 v[238:239], v2 offset0:237 offset1:236
	ds_read2_b32 v[240:241], v2 offset0:239 offset1:238
	ds_read_b32 v244, v2 offset:928
	ds_read_b32 v251, v2 offset:932
	v_lshl_or_b32 v0, s86, 5, v159
	v_sub_u32_e32 v2, v0, v228
	v_sub_u32_e32 v0, v0, v231
	s_waitcnt lgkmcnt(0)
	v_add_f32_e32 v243, v120, v243
	v_add_f32_e32 v242, v121, v242
	v_add_u32_e32 v120, 0, v0
	v_add_u32_e32 v121, 1, v0
	v_cmp_gt_u32_e32 vcc, 16, v120
	v_cmp_gt_u32_e64 s[42:43], 16, v121
	v_add_f32_e32 v246, v122, v246
	v_add_f32_e32 v245, v123, v245
	v_add_u32_e32 v122, 2, v0
	v_add_u32_e32 v123, 3, v0
	v_cndmask_b32_e32 v243, v218, v243, vcc
	v_cndmask_b32_e64 v242, v218, v242, s[42:43]
	v_cmp_gt_u32_e32 vcc, 16, v122
	v_cmp_gt_u32_e64 s[42:43], 16, v123
	v_add_f32_e32 v248, v116, v248
	v_add_f32_e32 v247, v117, v247
	v_add_u32_e32 v116, 4, v0
	v_add_u32_e32 v117, 5, v0
	v_cndmask_b32_e32 v246, v218, v246, vcc
	v_cndmask_b32_e64 v245, v218, v245, s[42:43]
	v_cmp_gt_u32_e32 vcc, 16, v116
	v_cmp_gt_u32_e64 s[42:43], 16, v117
	v_add_f32_e32 v250, v118, v250
	v_add_f32_e32 v249, v119, v249
	v_add_u32_e32 v118, 6, v0
	v_add_u32_e32 v119, 7, v0
	v_cndmask_b32_e32 v248, v218, v248, vcc
	v_cndmask_b32_e64 v247, v218, v247, s[42:43]
	v_cmp_gt_u32_e32 vcc, 16, v118
	v_cmp_gt_u32_e64 s[42:43], 16, v119
	v_add_f32_e32 v237, v130, v237
	v_add_f32_e32 v236, v131, v236
	v_add_u32_e32 v130, 2, v2
	v_add_u32_e32 v131, 3, v2
	v_cndmask_b32_e32 v250, v218, v250, vcc
	v_cndmask_b32_e64 v249, v218, v249, s[42:43]
	v_cmp_gt_u32_e32 vcc, 16, v130
	v_cmp_gt_u32_e64 s[42:43], 16, v131
	v_add_f32_e32 v239, v124, v239
	v_add_f32_e32 v238, v125, v238
	v_add_u32_e32 v124, 4, v2
	v_add_u32_e32 v125, 5, v2
	v_cndmask_b32_e32 v237, v218, v237, vcc
	v_cndmask_b32_e64 v236, v218, v236, s[42:43]
	v_cmp_gt_u32_e32 vcc, 16, v124
	v_cmp_gt_u32_e64 s[42:43], 16, v125
	v_add_f32_e32 v241, v126, v241
	v_add_f32_e32 v240, v127, v240
	v_add_u32_e32 v126, 6, v2
	v_add_u32_e32 v127, 7, v2
	v_cndmask_b32_e32 v239, v218, v239, vcc
	v_cndmask_b32_e64 v238, v218, v238, s[42:43]
	v_cmp_gt_u32_e32 vcc, 16, v126
	v_cmp_gt_u32_e64 s[42:43], 16, v127
	v_add_f32_e32 v251, v129, v251
	v_add_f32_e32 v244, v128, v244
	v_add_u32_e32 v129, 1, v2
	v_add_u32_e32 v128, 0, v2
	v_cndmask_b32_e32 v241, v218, v241, vcc
	v_cndmask_b32_e64 v240, v218, v240, s[42:43]
	v_cmp_gt_u32_e32 vcc, 16, v129
	v_cmp_gt_u32_e64 s[42:43], 16, v128
	s_nop 1
	v_cndmask_b32_e32 v0, v218, v251, vcc
	v_cndmask_b32_e64 v2, v218, v244, s[42:43]

.LBB0_332:
	v_sub_f32_e32 v120, v120, v128
	v_exp_f32_e32 v234, v120
	v_sub_f32_e32 v121, v121, v128
	v_exp_f32_e32 v241, v121
	v_sub_f32_e32 v121, v122, v128
	v_exp_f32_e32 v122, v121
	v_sub_f32_e32 v121, v123, v128
	v_exp_f32_e32 v123, v121
	v_sub_f32_e32 v116, v116, v128
	v_add_f32_e32 v120, 0, v234
	v_exp_f32_e32 v242, v116
	v_sub_f32_e32 v117, v117, v128
	v_add_f32_e32 v120, v241, v120
	v_exp_f32_e32 v243, v117
	v_sub_f32_e32 v117, v118, v128
	v_add_f32_e32 v120, v122, v120
	v_exp_f32_e32 v244, v117
	v_sub_f32_e32 v117, v119, v128
	v_add_f32_e32 v120, v123, v120
	v_exp_f32_e32 v119, v117
	v_add_f32_e32 v116, v242, v120
	v_add_f32_e32 v116, v243, v116
	v_add_f32_e32 v116, v244, v116
	v_add_f32_e32 v120, v119, v116
	v_fmac_f32_e32 v120, v138, v2
	v_add_f32_e32 v2, 0, v235
	v_add_f32_e32 v2, v129, v2
	v_add_f32_e32 v2, v130, v2
	v_add_f32_e32 v2, v131, v2
	v_add_f32_e32 v2, v237, v2
	v_add_f32_e32 v2, v238, v2
	v_add_f32_e32 v2, v239, v2
	v_add_f32_e32 v121, v240, v2
	v_fmac_f32_e32 v121, v139, v0
	v_add_u32_e32 v0, s85, v3
	v_mov_b32_e32 v139, v121
	v_mov_b32_e32 v138, v120
	v_cvt_pk_bf16_f32 v116, v234, v241
	v_cvt_pk_bf16_f32 v117, v122, v123
	v_cvt_pk_bf16_f32 v118, v242, v243
	v_cvt_pk_bf16_f32 v119, v244, v119
	v_add_u32_e32 v2, v0, v163
	ds_read_b64_tr_b16 v[238:239], v2 offset:32768
	v_add_u32_e32 v2, v0, v164
	ds_read_b64_tr_b16 v[240:241], v2 offset:33792
	v_add_u32_e32 v2, v0, v165
	ds_read_b64_tr_b16 v[242:243], v2 offset:32768
	v_add_u32_e32 v2, v0, v166
	ds_read_b64_tr_b16 v[244:245], v2 offset:33792
	v_add_u32_e32 v2, v0, v167
	ds_read_b64_tr_b16 v[246:247], v2 offset:32768
	v_add_u32_e32 v2, v0, v168
	ds_read_b64_tr_b16 v[248:249], v2 offset:33792
	s_waitcnt lgkmcnt(4)
	v_mfma_f32_16x16x32_bf16 v[64:67], v[238:241], v[124:127], v[64:67]
	v_mfma_f32_16x16x32_bf16 v[32:35], v[238:241], v[116:119], v[32:35]
	v_add_u32_e32 v2, v0, v169
	ds_read_b64_tr_b16 v[238:239], v2 offset:32768
	v_add_u32_e32 v2, v0, v170
	ds_read_b64_tr_b16 v[240:241], v2 offset:33792
	s_waitcnt lgkmcnt(4)
	v_mfma_f32_16x16x32_bf16 v[60:63], v[242:245], v[124:127], v[60:63]
	v_mfma_f32_16x16x32_bf16 v[28:31], v[242:245], v[116:119], v[28:31]
	v_add_u32_e32 v2, v0, v171
	ds_read_b64_tr_b16 v[242:243], v2 offset:32768
	v_add_u32_e32 v2, v0, v172
	ds_read_b64_tr_b16 v[244:245], v2 offset:33792
	s_waitcnt lgkmcnt(4)
	v_mfma_f32_16x16x32_bf16 v[56:59], v[246:249], v[124:127], v[56:59]
	v_mfma_f32_16x16x32_bf16 v[24:27], v[246:249], v[116:119], v[24:27]
	v_add_u32_e32 v2, v0, v173
	ds_read_b64_tr_b16 v[246:247], v2 offset:32768
	v_add_u32_e32 v2, v0, v174
	ds_read_b64_tr_b16 v[248:249], v2 offset:33792
	s_waitcnt lgkmcnt(4)
	v_mfma_f32_16x16x32_bf16 v[52:55], v[238:241], v[124:127], v[52:55]
	v_mfma_f32_16x16x32_bf16 v[20:23], v[238:241], v[116:119], v[20:23]
	v_add_u32_e32 v2, v0, v175
	ds_read_b64_tr_b16 v[238:239], v2 offset:32768
	v_add_u32_e32 v2, v0, v176
	ds_read_b64_tr_b16 v[240:241], v2 offset:33792
	s_waitcnt lgkmcnt(4)
	v_mfma_f32_16x16x32_bf16 v[48:51], v[242:245], v[124:127], v[48:51]
	v_mfma_f32_16x16x32_bf16 v[16:19], v[242:245], v[116:119], v[16:19]
	v_add_u32_e32 v2, v0, v177
	ds_read_b64_tr_b16 v[242:243], v2 offset:32768
	v_add_u32_e32 v2, v0, v178
	ds_read_b64_tr_b16 v[244:245], v2 offset:33792
	s_waitcnt lgkmcnt(4)
	v_mfma_f32_16x16x32_bf16 v[44:47], v[246:249], v[124:127], v[44:47]
	v_mfma_f32_16x16x32_bf16 v[12:15], v[246:249], v[116:119], v[12:15]
	s_waitcnt lgkmcnt(2)
	v_mfma_f32_16x16x32_bf16 v[40:43], v[238:241], v[124:127], v[40:43]
	v_mfma_f32_16x16x32_bf16 v[8:11], v[238:241], v[116:119], v[8:11]
	s_waitcnt lgkmcnt(0)
	v_mfma_f32_16x16x32_bf16 v[36:39], v[242:245], v[124:127], v[36:39]
	v_mfma_f32_16x16x32_bf16 v[4:7], v[242:245], v[116:119], v[4:7]
	s_branch .LBB0_334
